# adaLN k-loop: all 16 W-row loads issued at loop top (7 late loads hoisted into fresh VGPRs, waits recounted)
# speedup vs baseline: 1.0142x; 1.0091x over previous
; #define LAS __attribute__((address_space(3)))
; __device__ __forceinline__ void adaln_unit(const Args& a, LAS unsigned char* lds, int unit, int tid, int wave, int lane) {
;     ...
;         for (int k = 0; k < 128; k += 16) {
;             float w[16];
; #pragma unroll
;             for (int e = 0; e < 16; ++e) w[e] = W[(size_t)(kh * 1024 + kb + k + e) * N + jc];
; #pragma unroll
;             for (int q = 0; q < 4; ++q)
; #pragma unroll
;                 for (int r = 0; r < 18; ++r) { const f32x4 s = *(const LAS f32x4*)(sc + r * 1024 + kb + k + 4 * q); acc[r] += s[0] * w[4 * q] + s[1] * w[4 * q + 1] + s[2] * w[4 * q + 2] + s[3] * w[4 * q + 3]; }
.LBB0_20:
	s_add_i32 s34, s83, 0xffff0000
	s_add_i32 s58, s83, 0xffff1000
	s_add_i32 s84, s83, 0xffff2000
	s_add_i32 s85, s83, 0xffff3000
	s_add_i32 s86, s83, 0xffff4000
	s_add_i32 s87, s83, 0xffff5000
	v_mov_b32_e32 v102, s83
	v_mov_b32_e32 v14, s34
	v_mov_b32_e32 v18, s58
	v_mov_b32_e32 v19, s84
	v_mov_b32_e32 v22, s85
	v_mov_b32_e32 v23, s86
	v_mov_b32_e32 v30, s87
	ds_read_b128 v[10:13], v102
	ds_read_b128 v[2:5], v102 offset:16
	ds_read_b128 v[26:29], v102 offset:4096
	ds_read_b128 v[6:9], v102 offset:4112
	ds_read_b128 v[14:17], v14
	ds_read_b128 v[34:37], v18
	ds_read_b128 v[18:21], v19
	ds_read_b128 v[72:75], v22
	ds_read_b128 v[22:25], v23
	ds_read_b128 v[76:79], v30
	s_add_i32 vcc_hi, s83, 0xffff7000
	s_add_i32 vcc_lo, s83, 0xffff6000
	v_mov_b32_e32 v68, vcc_hi
	v_mov_b32_e32 v38, vcc_lo
	s_waitcnt lgkmcnt(2)
	v_mov_b32_e32 v70, v72
	v_mov_b32_e32 v71, v18
	v_mov_b32_e32 v18, v73
	s_waitcnt lgkmcnt(0)
	v_mov_b32_e32 v72, v76
	v_mov_b32_e32 v73, v22
	v_mov_b32_e32 v22, v77
	v_mov_b32_e32 v64, v78
	v_mov_b32_e32 v65, v24
	v_mov_b32_e32 v24, v79
	ds_read_b128 v[76:79], v68
	v_mov_b32_e32 v32, v26
	v_mov_b32_e32 v33, v10
	v_mov_b32_e32 v10, v27
	v_mov_b32_e32 v30, v28
	v_mov_b32_e32 v31, v12
	v_mov_b32_e32 v12, v29
	ds_read_b128 v[26:29], v38
	s_add_i32 s58, s83, 0xffff9000
	v_mov_b32_e32 v66, v34
	v_mov_b32_e32 v34, v36
	v_mov_b32_e32 v36, v74
	s_waitcnt lgkmcnt(1)
	v_mov_b32_e32 v74, v76
	s_add_i32 s34, s83, 0xffff8000
	v_mov_b32_e32 v76, s58
	v_mov_b32_e32 v67, v14
	v_mov_b32_e32 v14, v35
	v_mov_b32_e32 v35, v16
	v_mov_b32_e32 v16, v37
	v_mov_b32_e32 v37, v20
	v_mov_b32_e32 v20, v75
	s_waitcnt lgkmcnt(0)
	v_mov_b32_e32 v75, v26
	v_mov_b32_e32 v26, v77
	v_mov_b32_e32 v68, v78
	v_mov_b32_e32 v69, v28
	v_mov_b32_e32 v28, v79
	v_mov_b32_e32 v38, s34
	ds_read_b128 v[76:79], v76
	ds_read_b128 v[88:91], v38
	s_add_i32 s58, s83, 0xffffb000
	s_add_i32 s34, s83, 0xffffa000
	v_mov_b32_e32 v38, s34
	s_waitcnt lgkmcnt(1)
	v_mov_b32_e32 v80, v76
	v_mov_b32_e32 v76, s58
	s_waitcnt lgkmcnt(0)
	v_mov_b32_e32 v81, v88
	v_mov_b32_e32 v88, v77
	v_mov_b32_e32 v96, v78
	v_mov_b32_e32 v97, v90
	v_mov_b32_e32 v90, v79
	ds_read_b128 v[76:79], v76
	ds_read_b128 v[92:95], v38
	s_add_i32 s58, s83, 0xffffd000
	s_add_i32 s34, s83, 0xffffc000
	v_mov_b32_e32 v38, s34
	s_waitcnt lgkmcnt(1)
	v_mov_b32_e32 v112, v76
	v_mov_b32_e32 v76, s58
	s_waitcnt lgkmcnt(0)
	v_mov_b32_e32 v113, v92
	v_mov_b32_e32 v92, v77
	v_mov_b32_e32 v114, v78
	v_mov_b32_e32 v115, v94
	v_mov_b32_e32 v94, v79
	ds_read_b128 v[76:79], v76
	ds_read_b128 v[104:107], v38
	s_add_i32 s34, s83, 0xffffe000
	s_add_i32 s58, s83, 0xfffff000
	v_mov_b32_e32 v38, s34
	s_waitcnt lgkmcnt(1)
	v_mov_b32_e32 v116, v76
	v_mov_b32_e32 v76, s58
	s_waitcnt lgkmcnt(0)
	v_mov_b32_e32 v117, v104
	v_mov_b32_e32 v104, v77
	v_mov_b32_e32 v118, v78
	v_mov_b32_e32 v119, v106
	v_mov_b32_e32 v106, v79
	ds_read_b128 v[76:79], v76
	ds_read_b128 v[108:111], v38
	s_add_i32 s58, s83, 0xffff1010
	s_add_i32 s34, s83, 0xffff0010
	s_add_i32 s82, s82, 16
	s_waitcnt lgkmcnt(1)
	v_mov_b32_e32 v120, v76
	s_waitcnt lgkmcnt(0)
	v_mov_b32_e32 v121, v108
	v_mov_b32_e32 v108, v77
	v_mov_b32_e32 v76, v78
	v_mov_b32_e32 v77, v110
	v_mov_b32_e32 v110, v79
	v_lshl_add_u64 v[78:79], v[44:45], 0, s[74:75]
	global_load_dword v122, v[78:79], off
	v_lshl_add_u64 v[78:79], v[78:79], 0, s[74:75]
	v_lshl_add_u64 v[82:83], v[78:79], 0, s[74:75]
	global_load_dword v78, v[78:79], off
	s_nop 0
	global_load_dword v124, v[82:83], off
	v_lshl_add_u64 v[82:83], v[82:83], 0, s[74:75]
	v_lshl_add_u64 v[98:99], v[82:83], 0, s[74:75]
	global_load_dword v84, v[82:83], off
	global_load_dword v86, v[98:99], off
	v_lshl_add_u64 v[82:83], v[98:99], 0, s[74:75]
	v_lshl_add_u64 v[100:101], v[82:83], 0, s[74:75]
	global_load_dword v82, v[82:83], off
	s_nop 0
	global_load_dword v98, v[100:101], off
	v_lshl_add_u64 v[100:101], v[100:101], 0, s[74:75]
	global_load_dword v126, v[44:45], off
	global_load_dword v38, v[100:101], off
	v_lshl_add_u64 v[100:101], v[100:101], 0, s[74:75]
	v_lshl_add_u64 v[218:219], v[100:101], 0, s[74:75]
	v_lshl_add_u64 v[220:221], v[218:219], 0, s[74:75]
	v_lshl_add_u64 v[222:223], v[220:221], 0, s[74:75]
	v_lshl_add_u64 v[224:225], v[222:223], 0, s[74:75]
	v_lshl_add_u64 v[226:227], v[224:225], 0, s[74:75]
	v_lshl_add_u64 v[228:229], v[226:227], 0, s[74:75]
	global_load_dword v204, v[100:101], off
	global_load_dword v206, v[218:219], off
	global_load_dword v208, v[220:221], off
	global_load_dword v210, v[222:223], off
	global_load_dword v212, v[224:225], off
	global_load_dword v214, v[226:227], off
	global_load_dword v216, v[228:229], off
	v_lshl_add_u64 v[44:45], v[44:45], 0, s[78:79]
	s_waitcnt vmcnt(15)
	v_pk_mul_f32 v[14:15], v[122:123], v[14:15] op_sel_hi:[0,1]
	v_pk_mul_f32 v[26:27], v[122:123], v[26:27] op_sel_hi:[0,1]
	v_pk_mul_f32 v[18:19], v[122:123], v[18:19] op_sel_hi:[0,1]
	v_pk_mul_f32 v[22:23], v[122:123], v[22:23] op_sel_hi:[0,1]
	v_pk_mul_f32 v[10:11], v[122:123], v[10:11] op_sel_hi:[0,1]
	s_waitcnt vmcnt(8)
; #define LAS __attribute__((address_space(3)))
; __device__ __forceinline__ void adaln_unit(const Args& a, LAS unsigned char* lds, int unit, int tid, int wave, int lane) {
;     ...
; #pragma unroll
;             for (int q = 0; q < 4; ++q)
; #pragma unroll
;                 for (int r = 0; r < 18; ++r) { const f32x4 s = *(const LAS f32x4*)(sc + r * 1024 + kb + k + 4 * q); acc[r] += s[0] * w[4 * q] + s[1] * w[4 * q + 1] + s[2] * w[4 * q + 2] + s[3] * w[4 * q + 3]; }
	v_pk_fma_f32 v[14:15], v[126:127], v[66:67], v[14:15] op_sel_hi:[0,1,1]
	v_pk_fma_f32 v[26:27], v[126:127], v[74:75], v[26:27] op_sel_hi:[0,1,1]
	v_pk_mul_f32 v[74:75], v[122:123], v[108:109] op_sel_hi:[0,1]
	v_pk_fma_f32 v[18:19], v[126:127], v[70:71], v[18:19] op_sel_hi:[0,1,1]
	v_pk_fma_f32 v[22:23], v[126:127], v[72:73], v[22:23] op_sel_hi:[0,1,1]
	v_pk_mul_f32 v[66:67], v[122:123], v[88:89] op_sel_hi:[0,1]
	v_pk_mul_f32 v[70:71], v[122:123], v[92:93] op_sel_hi:[0,1]
	v_pk_mul_f32 v[72:73], v[122:123], v[104:105] op_sel_hi:[0,1]
	v_pk_fma_f32 v[74:75], v[126:127], v[120:121], v[74:75] op_sel_hi:[0,1,1]
	v_pk_fma_f32 v[10:11], v[126:127], v[32:33], v[10:11] op_sel_hi:[0,1,1]
	v_pk_fma_f32 v[14:15], v[78:79], v[34:35], v[14:15] op_sel_hi:[0,1,1]
	v_pk_fma_f32 v[66:67], v[126:127], v[80:81], v[66:67] op_sel_hi:[0,1,1]
	v_pk_fma_f32 v[70:71], v[126:127], v[112:113], v[70:71] op_sel_hi:[0,1,1]
	v_pk_fma_f32 v[72:73], v[126:127], v[116:117], v[72:73] op_sel_hi:[0,1,1]
	v_pk_fma_f32 v[22:23], v[78:79], v[64:65], v[22:23] op_sel_hi:[0,1,1]
	v_pk_fma_f32 v[80:81], v[78:79], v[76:77], v[74:75] op_sel_hi:[0,1,1]
	v_pk_fma_f32 v[10:11], v[78:79], v[30:31], v[10:11] op_sel_hi:[0,1,1]
	v_pk_fma_f32 v[64:65], v[124:125], v[16:17], v[14:15] op_sel_hi:[0,1,1]
	v_mov_b32_e32 v14, s58
	v_pk_fma_f32 v[18:19], v[78:79], v[36:37], v[18:19] op_sel_hi:[0,1,1]
	v_pk_fma_f32 v[26:27], v[78:79], v[68:69], v[26:27] op_sel_hi:[0,1,1]
	v_pk_fma_f32 v[32:33], v[78:79], v[96:97], v[66:67] op_sel_hi:[0,1,1]
	v_pk_fma_f32 v[34:35], v[78:79], v[114:115], v[70:71] op_sel_hi:[0,1,1]
	v_pk_fma_f32 v[36:37], v[78:79], v[118:119], v[72:73] op_sel_hi:[0,1,1]
	v_pk_fma_f32 v[78:79], v[124:125], v[110:111], v[80:81] op_sel_hi:[0,1,1]
	v_pk_fma_f32 v[80:81], v[124:125], v[12:13], v[10:11] op_sel_hi:[0,1,1]
	ds_read_b128 v[10:13], v14
	v_pk_fma_f32 v[66:67], v[124:125], v[20:21], v[18:19] op_sel_hi:[0,1,1]
	v_mov_b32_e32 v18, s34
	v_mov_b32_e32 v16, v6
	v_mov_b32_e32 v17, v2
	v_mov_b32_e32 v2, v7
	v_mov_b32_e32 v14, v8
	v_mov_b32_e32 v15, v4
	v_mov_b32_e32 v4, v9
	ds_read_b128 v[6:9], v18
	s_add_i32 s34, s83, 0xffff2010
	s_waitcnt lgkmcnt(1)
	v_mov_b32_e32 v20, v10
	v_mov_b32_e32 v10, s34
	s_add_i32 s34, s83, 0xffff4010
	v_mov_b32_e32 v30, s34
	s_add_i32 s34, s83, 0xffff6010
	v_pk_fma_f32 v[74:75], v[124:125], v[94:95], v[34:35] op_sel_hi:[0,1,1]
	v_mov_b32_e32 v34, s34
	s_add_i32 s34, s83, 0xffff8010
	s_add_i32 s58, s83, 0xffff3010
	v_mov_b32_e32 v83, s34
	v_pk_fma_f32 v[72:73], v[124:125], v[90:91], v[32:33] op_sel_hi:[0,1,1]
	ds_read_b128 v[88:91], v83
	s_waitcnt lgkmcnt(1)
	v_mov_b32_e32 v21, v6
	v_mov_b32_e32 v6, v11
	v_mov_b32_e32 v11, s58
	v_pk_fma_f32 v[70:71], v[124:125], v[28:29], v[26:27] op_sel_hi:[0,1,1]
	ds_read_b128 v[26:29], v11
	v_pk_fma_f32 v[76:77], v[124:125], v[106:107], v[36:37] op_sel_hi:[0,1,1]
	v_mov_b32_e32 v18, v12
	v_mov_b32_e32 v19, v8
	v_mov_b32_e32 v8, v13
	ds_read_b128 v[34:37], v34
	ds_read_b128 v[10:13], v10
	ds_read_b128 v[30:33], v30
	s_add_i32 s58, s83, 0xffff5010
	v_pk_fma_f32 v[68:69], v[124:125], v[24:25], v[22:23] op_sel_hi:[0,1,1]
	s_waitcnt lgkmcnt(3)
	v_mov_b32_e32 v24, v26
	v_mov_b32_e32 v26, s58
	s_waitcnt lgkmcnt(1)
	v_mov_b32_e32 v25, v10
	v_mov_b32_e32 v10, v27
	v_mov_b32_e32 v22, v28
	v_mov_b32_e32 v23, v12
	v_mov_b32_e32 v12, v29
	ds_read_b128 v[26:29], v26
	s_add_i32 s34, s83, 0xffffa010
	s_add_i32 s58, s83, 0xffff7010
	v_mov_b32_e32 v83, s34
	ds_read_b128 v[92:95], v83
	s_waitcnt lgkmcnt(1)
	v_mov_b32_e32 v96, v26
	v_mov_b32_e32 v26, s58
	v_mov_b32_e32 v97, v30
	v_mov_b32_e32 v30, v27
	v_mov_b32_e32 v112, v28
	v_mov_b32_e32 v113, v32
	v_mov_b32_e32 v32, v29
	ds_read_b128 v[26:29], v26
	s_add_i32 s34, s83, 0xffffc010
	s_add_i32 s58, s83, 0xffff9010
	v_mov_b32_e32 v83, s34
	ds_read_b128 v[104:107], v83
	s_waitcnt lgkmcnt(1)
	v_mov_b32_e32 v114, v26
	v_mov_b32_e32 v26, s58
	v_mov_b32_e32 v115, v34
	v_mov_b32_e32 v34, v27
	v_mov_b32_e32 v116, v28
	v_mov_b32_e32 v117, v36
	v_mov_b32_e32 v36, v29
	ds_read_b128 v[26:29], v26
	s_add_i32 s34, s83, 0xffffe010
	s_add_i32 s58, s83, 0xffffb010
	v_mov_b32_e32 v83, s34
	ds_read_b128 v[108:111], v83
	s_waitcnt lgkmcnt(1)
	v_mov_b32_e32 v118, v26
	v_mov_b32_e32 v26, s58
	v_mov_b32_e32 v119, v88
	v_mov_b32_e32 v88, v27
	v_mov_b32_e32 v120, v28
	v_mov_b32_e32 v121, v90
	v_mov_b32_e32 v90, v29
	ds_read_b128 v[26:29], v26
	s_add_i32 s58, s83, 0xffffd010
	v_mov_b32_e32 v123, v92
	v_mov_b32_e32 v125, v94
	v_mov_b32_e32 v127, v104
	s_waitcnt lgkmcnt(0)
	v_mov_b32_e32 v122, v26
	v_mov_b32_e32 v26, s58
	v_mov_b32_e32 v92, v27
	v_mov_b32_e32 v124, v28
	v_mov_b32_e32 v94, v29
	ds_read_b128 v[26:29], v26
	s_add_i32 s58, s83, 0xfffff010
	v_mov_b32_e32 v129, v106
	v_mov_b32_e32 v131, v108
	v_pk_mul_f32 v[6:7], v[86:87], v[6:7] op_sel_hi:[0,1]
	s_waitcnt lgkmcnt(0)
	v_mov_b32_e32 v126, v26
	v_mov_b32_e32 v26, s58
	v_mov_b32_e32 v104, v27
	v_mov_b32_e32 v128, v28
	v_mov_b32_e32 v106, v29
	ds_read_b128 v[26:29], v26
	v_pk_mul_f32 v[10:11], v[86:87], v[10:11] op_sel_hi:[0,1]
	v_pk_fma_f32 v[6:7], v[84:85], v[20:21], v[6:7] op_sel_hi:[0,1,1]
	v_pk_fma_f32 v[10:11], v[84:85], v[24:25], v[10:11] op_sel_hi:[0,1,1]
	v_pk_mul_f32 v[20:21], v[86:87], v[30:31] op_sel_hi:[0,1]
	s_waitcnt lgkmcnt(0)
; #define LAS __attribute__((address_space(3)))
; __device__ __forceinline__ void adaln_unit(const Args& a, LAS unsigned char* lds, int unit, int tid, int wave, int lane) {
;     ...
; #pragma unroll
;             for (int q = 0; q < 4; ++q)
; #pragma unroll
;                 for (int r = 0; r < 18; ++r) { const f32x4 s = *(const LAS f32x4*)(sc + r * 1024 + kb + k + 4 * q); acc[r] += s[0] * w[4 * q] + s[1] * w[4 * q + 1] + s[2] * w[4 * q + 2] + s[3] * w[4 * q + 3]; }
;         }
	v_mov_b32_e32 v108, v27
	v_mov_b32_e32 v130, v26
	v_mov_b32_e32 v26, v28
	v_mov_b32_e32 v27, v110
	v_mov_b32_e32 v110, v29
	v_pk_mul_f32 v[24:25], v[86:87], v[34:35] op_sel_hi:[0,1]
	v_pk_mul_f32 v[28:29], v[86:87], v[88:89] op_sel_hi:[0,1]
	v_pk_mul_f32 v[30:31], v[86:87], v[92:93] op_sel_hi:[0,1]
	v_pk_mul_f32 v[34:35], v[86:87], v[104:105] op_sel_hi:[0,1]
	v_pk_mul_f32 v[88:89], v[86:87], v[108:109] op_sel_hi:[0,1]
	v_pk_mul_f32 v[2:3], v[86:87], v[2:3] op_sel_hi:[0,1]
	v_pk_fma_f32 v[20:21], v[84:85], v[96:97], v[20:21] op_sel_hi:[0,1,1]
	v_pk_fma_f32 v[24:25], v[84:85], v[114:115], v[24:25] op_sel_hi:[0,1,1]
	v_pk_fma_f32 v[28:29], v[84:85], v[118:119], v[28:29] op_sel_hi:[0,1,1]
	v_pk_fma_f32 v[30:31], v[84:85], v[122:123], v[30:31] op_sel_hi:[0,1,1]
	v_pk_fma_f32 v[34:35], v[84:85], v[126:127], v[34:35] op_sel_hi:[0,1,1]
	v_pk_fma_f32 v[88:89], v[84:85], v[130:131], v[88:89] op_sel_hi:[0,1,1]
	v_pk_fma_f32 v[2:3], v[84:85], v[16:17], v[2:3] op_sel_hi:[0,1,1]
	v_pk_fma_f32 v[6:7], v[82:83], v[18:19], v[6:7] op_sel_hi:[0,1,1]
	v_pk_fma_f32 v[10:11], v[82:83], v[22:23], v[10:11] op_sel_hi:[0,1,1]
	v_pk_fma_f32 v[16:17], v[82:83], v[112:113], v[20:21] op_sel_hi:[0,1,1]
	v_pk_fma_f32 v[18:19], v[82:83], v[116:117], v[24:25] op_sel_hi:[0,1,1]
	v_pk_fma_f32 v[20:21], v[82:83], v[120:121], v[28:29] op_sel_hi:[0,1,1]
	v_pk_fma_f32 v[22:23], v[82:83], v[124:125], v[30:31] op_sel_hi:[0,1,1]
	v_pk_fma_f32 v[24:25], v[82:83], v[128:129], v[34:35] op_sel_hi:[0,1,1]
	v_pk_fma_f32 v[26:27], v[82:83], v[26:27], v[88:89] op_sel_hi:[0,1,1]
	v_pk_fma_f32 v[2:3], v[82:83], v[14:15], v[2:3] op_sel_hi:[0,1,1]
	v_pk_fma_f32 v[82:83], v[98:99], v[8:9], v[6:7] op_sel_hi:[0,1,1]
	v_pk_fma_f32 v[84:85], v[98:99], v[12:13], v[10:11] op_sel_hi:[0,1,1]
	v_pk_fma_f32 v[86:87], v[98:99], v[32:33], v[16:17] op_sel_hi:[0,1,1]
	v_pk_fma_f32 v[88:89], v[98:99], v[36:37], v[18:19] op_sel_hi:[0,1,1]
	v_pk_fma_f32 v[90:91], v[98:99], v[90:91], v[20:21] op_sel_hi:[0,1,1]
	v_pk_fma_f32 v[92:93], v[98:99], v[94:95], v[22:23] op_sel_hi:[0,1,1]
	v_pk_fma_f32 v[94:95], v[98:99], v[106:107], v[24:25] op_sel_hi:[0,1,1]
	v_pk_fma_f32 v[96:97], v[98:99], v[110:111], v[26:27] op_sel_hi:[0,1,1]
	v_pk_fma_f32 v[98:99], v[98:99], v[4:5], v[2:3] op_sel_hi:[0,1,1]
	ds_read_b128 v[14:17], v102 offset:4128
	ds_read_b128 v[6:9], v102 offset:4144
	ds_read_b128 v[10:13], v102 offset:32
	ds_read_b128 v[2:5], v102 offset:48
	s_add_i32 s34, s83, 0xffff0020
	s_add_i32 s58, s83, 0xffff1020
	s_waitcnt lgkmcnt(3)
	v_mov_b32_e32 v28, v14
	s_waitcnt lgkmcnt(1)
	v_mov_b32_e32 v29, v10
	v_mov_b32_e32 v10, v15
	v_mov_b32_e32 v14, s34
	v_mov_b32_e32 v15, s58
	v_mov_b32_e32 v26, v16
	v_mov_b32_e32 v27, v12
	v_mov_b32_e32 v12, v17
	ds_read_b128 v[18:21], v15
	ds_read_b128 v[14:17], v14
	s_add_i32 s58, s83, 0xffff3020
	s_add_i32 s34, s83, 0xffff2020
	v_pk_add_f32 v[60:61], v[60:61], v[66:67]
	s_waitcnt lgkmcnt(1)
	v_mov_b32_e32 v32, v18
	s_waitcnt lgkmcnt(0)
	v_mov_b32_e32 v33, v14
	v_mov_b32_e32 v14, v19
	v_mov_b32_e32 v19, s58
	ds_read_b128 v[22:25], v19
	v_mov_b32_e32 v18, s34
	v_mov_b32_e32 v30, v20
	v_mov_b32_e32 v31, v16
	v_mov_b32_e32 v16, v21
	ds_read_b128 v[18:21], v18
	s_add_i32 s34, s83, 0xffff4020
	s_waitcnt lgkmcnt(1)
	v_mov_b32_e32 v36, v22
	v_mov_b32_e32 v22, s34
	s_add_i32 s34, s83, 0xffff6020
	s_add_i32 s58, s83, 0xffff5020
	v_mov_b32_e32 v106, s34
	s_add_i32 s34, s83, 0xffff8020
	ds_read_b128 v[106:109], v106
	s_waitcnt lgkmcnt(1)
	v_mov_b32_e32 v37, v18
	v_mov_b32_e32 v18, v23
	v_mov_b32_e32 v23, s58
	v_mov_b32_e32 v110, s34
	s_add_i32 s34, s83, 0xffffa020
	ds_read_b128 v[102:105], v23
	v_mov_b32_e32 v114, s34
	v_mov_b32_e32 v34, v24
	v_mov_b32_e32 v35, v20
	v_mov_b32_e32 v20, v25
	ds_read_b128 v[114:117], v114
	ds_read_b128 v[22:25], v22
	ds_read_b128 v[110:113], v110
	s_add_i32 s58, s83, 0xffff7020
	s_waitcnt lgkmcnt(3)
	v_mov_b32_e32 v126, v102
	v_mov_b32_e32 v102, s58
	s_waitcnt lgkmcnt(1)
	v_mov_b32_e32 v127, v22
	v_mov_b32_e32 v22, v103
	v_mov_b32_e32 v128, v104
	v_mov_b32_e32 v129, v24
	v_mov_b32_e32 v24, v105
	ds_read_b128 v[102:105], v102
	s_add_i32 s34, s83, 0xffffc020
	s_add_i32 s58, s83, 0xffff9020
	v_mov_b32_e32 v118, s34
	ds_read_b128 v[118:121], v118
	s_waitcnt lgkmcnt(1)
	v_mov_b32_e32 v130, v102
	v_mov_b32_e32 v102, s58
	v_mov_b32_e32 v131, v106
	v_mov_b32_e32 v106, v103
	v_mov_b32_e32 v132, v104
	v_mov_b32_e32 v133, v108
	v_mov_b32_e32 v108, v105
	ds_read_b128 v[102:105], v102
	s_add_i32 s34, s83, 0xffffe020
	s_add_i32 s58, s83, 0xffffb020
	v_mov_b32_e32 v122, s34
	ds_read_b128 v[122:125], v122
	s_waitcnt lgkmcnt(1)
	v_mov_b32_e32 v134, v102
	v_mov_b32_e32 v102, s58
	v_mov_b32_e32 v135, v110
	v_mov_b32_e32 v110, v103
	v_mov_b32_e32 v136, v104
	v_mov_b32_e32 v137, v112
	v_mov_b32_e32 v112, v105
	ds_read_b128 v[102:105], v102
	s_add_i32 s58, s83, 0xffffd020
	v_mov_b32_e32 v139, v114
	v_mov_b32_e32 v141, v116
	v_mov_b32_e32 v143, v118
	s_waitcnt lgkmcnt(0)
	v_mov_b32_e32 v138, v102
	v_mov_b32_e32 v102, s58
	v_mov_b32_e32 v114, v103
	v_mov_b32_e32 v140, v104
	v_mov_b32_e32 v116, v105
	ds_read_b128 v[102:105], v102
	s_add_i32 s58, s83, 0xfffff020
	v_mov_b32_e32 v145, v120
	v_mov_b32_e32 v151, v122
	s_add_i32 s34, s83, 0xffff0030
	s_waitcnt lgkmcnt(0)
	v_mov_b32_e32 v142, v102
	v_mov_b32_e32 v102, s58
	v_mov_b32_e32 v118, v103
	v_mov_b32_e32 v144, v104
	v_mov_b32_e32 v120, v105
	ds_read_b128 v[102:105], v102
	s_add_i32 s58, s83, 0xffff1030
	v_pk_add_f32 v[58:59], v[58:59], v[68:69]
	v_pk_add_f32 v[56:57], v[56:57], v[70:71]
	v_pk_add_f32 v[54:55], v[54:55], v[72:73]
	s_waitcnt lgkmcnt(0)
; #define LAS __attribute__((address_space(3)))
; __device__ __forceinline__ void adaln_unit(const Args& a, LAS unsigned char* lds, int unit, int tid, int wave, int lane) {
;     ...
;         for (int k = 0; k < 128; k += 16) {
;             float w[16];
; #pragma unroll
;             for (int e = 0; e < 16; ++e) w[e] = W[(size_t)(kh * 1024 + kb + k + e) * N + jc];
; #pragma unroll
;             for (int q = 0; q < 4; ++q)
; #pragma unroll
;                 for (int r = 0; r < 18; ++r) { const f32x4 s = *(const LAS f32x4*)(sc + r * 1024 + kb + k + 4 * q); acc[r] += s[0] * w[4 * q] + s[1] * w[4 * q + 1] + s[2] * w[4 * q + 2] + s[3] * w[4 * q + 3]; }
	v_mov_b32_e32 v150, v102
	v_mov_b32_e32 v102, v104
	s_nop 0
	v_lshl_add_u64 v[100:101], v[100:101], 0, s[74:75]
	s_nop 0
	v_mov_b32_e32 v122, v103
	v_mov_b32_e32 v103, v124
	v_mov_b32_e32 v124, v105
	v_pk_add_f32 v[52:53], v[52:53], v[74:75]
	v_pk_add_f32 v[50:51], v[50:51], v[76:77]
	v_pk_add_f32 v[48:49], v[48:49], v[78:79]
	v_pk_add_f32 v[46:47], v[46:47], v[80:81]
	v_pk_add_f32 v[60:61], v[60:61], v[84:85]
	v_pk_add_f32 v[58:59], v[58:59], v[86:87]
	v_pk_add_f32 v[56:57], v[56:57], v[88:89]
	v_pk_add_f32 v[54:55], v[54:55], v[90:91]
	v_pk_add_f32 v[66:67], v[50:51], v[94:95]
	v_pk_add_f32 v[68:69], v[48:49], v[96:97]
	v_pk_add_f32 v[70:71], v[46:47], v[98:99]
	s_waitcnt vmcnt(6)
	v_pk_mul_f32 v[14:15], v[204:205], v[14:15] op_sel_hi:[0,1]
	v_pk_mul_f32 v[10:11], v[204:205], v[10:11] op_sel_hi:[0,1]
	v_pk_fma_f32 v[14:15], v[38:39], v[32:33], v[14:15] op_sel_hi:[0,1,1]
	v_pk_mul_f32 v[32:33], v[204:205], v[106:107] op_sel_hi:[0,1]
	v_pk_mul_f32 v[106:107], v[204:205], v[114:115] op_sel_hi:[0,1]
	v_pk_mul_f32 v[114:115], v[204:205], v[122:123] op_sel_hi:[0,1]
	v_pk_fma_f32 v[10:11], v[38:39], v[28:29], v[10:11] op_sel_hi:[0,1,1]
	v_lshl_add_u64 v[122:123], v[100:101], 0, s[74:75]
	s_waitcnt vmcnt(5)
	v_pk_fma_f32 v[10:11], v[206:207], v[26:27], v[10:11] op_sel_hi:[0,1,1]
	s_nop 0
	v_pk_mul_f32 v[18:19], v[204:205], v[18:19] op_sel_hi:[0,1]
	v_pk_fma_f32 v[18:19], v[38:39], v[36:37], v[18:19] op_sel_hi:[0,1,1]
	v_pk_mul_f32 v[36:37], v[204:205], v[110:111] op_sel_hi:[0,1]
	v_pk_mul_f32 v[110:111], v[204:205], v[118:119] op_sel_hi:[0,1]
	v_pk_fma_f32 v[32:33], v[38:39], v[130:131], v[32:33] op_sel_hi:[0,1,1]
	v_pk_fma_f32 v[36:37], v[38:39], v[134:135], v[36:37] op_sel_hi:[0,1,1]
	v_pk_fma_f32 v[110:111], v[38:39], v[142:143], v[110:111] op_sel_hi:[0,1,1]
	v_pk_fma_f32 v[106:107], v[38:39], v[138:139], v[106:107] op_sel_hi:[0,1,1]
	v_pk_fma_f32 v[14:15], v[206:207], v[30:31], v[14:15] op_sel_hi:[0,1,1]
	v_pk_fma_f32 v[18:19], v[206:207], v[34:35], v[18:19] op_sel_hi:[0,1,1]
	v_pk_fma_f32 v[28:29], v[206:207], v[132:133], v[32:33] op_sel_hi:[0,1,1]
	v_pk_fma_f32 v[30:31], v[206:207], v[136:137], v[36:37] op_sel_hi:[0,1,1]
	v_pk_fma_f32 v[34:35], v[206:207], v[144:145], v[110:111] op_sel_hi:[0,1,1]
	v_pk_fma_f32 v[32:33], v[206:207], v[140:141], v[106:107] op_sel_hi:[0,1,1]
	v_pk_fma_f32 v[114:115], v[38:39], v[150:151], v[114:115] op_sel_hi:[0,1,1]
	v_mov_b32_e32 v118, v8
	v_mov_b32_e32 v119, v4
	v_mov_b32_e32 v4, v9
	v_pk_fma_f32 v[36:37], v[206:207], v[102:103], v[114:115] op_sel_hi:[0,1,1]
	v_pk_mul_f32 v[22:23], v[204:205], v[22:23] op_sel_hi:[0,1]
	v_pk_fma_f32 v[22:23], v[38:39], v[126:127], v[22:23] op_sel_hi:[0,1,1]
	v_pk_fma_f32 v[22:23], v[206:207], v[128:129], v[22:23] op_sel_hi:[0,1,1]
	v_lshl_add_u64 v[122:123], v[122:123], 0, s[74:75]
	s_nop 0
	v_lshl_add_u64 v[122:123], v[122:123], 0, s[74:75]
	s_waitcnt vmcnt(4)
	v_pk_fma_f32 v[106:107], v[208:209], v[108:109], v[28:29] op_sel_hi:[0,1,1]
	v_pk_fma_f32 v[108:109], v[208:209], v[112:113], v[30:31] op_sel_hi:[0,1,1]
	v_pk_fma_f32 v[112:113], v[208:209], v[120:121], v[34:35] op_sel_hi:[0,1,1]
	v_mov_b32_e32 v120, v6
	v_mov_b32_e32 v6, s58
	v_pk_fma_f32 v[110:111], v[208:209], v[116:117], v[32:33] op_sel_hi:[0,1,1]
	v_pk_fma_f32 v[116:117], v[208:209], v[12:13], v[10:11] op_sel_hi:[0,1,1]
	v_mov_b32_e32 v121, v2
	v_mov_b32_e32 v2, v7
	v_mov_b32_e32 v10, s34
	ds_read_b128 v[6:9], v6
	v_pk_fma_f32 v[102:103], v[208:209], v[20:21], v[18:19] op_sel_hi:[0,1,1]
	ds_read_b128 v[18:21], v10
	s_add_i32 s34, s83, 0xffff2030
	s_add_i32 s58, s83, 0xffff3030
	s_waitcnt lgkmcnt(1)
	v_mov_b32_e32 v126, v6
	v_mov_b32_e32 v10, s34
	v_mov_b32_e32 v6, s58
	v_pk_fma_f32 v[104:105], v[208:209], v[24:25], v[22:23] op_sel_hi:[0,1,1]
	v_pk_fma_f32 v[114:115], v[208:209], v[124:125], v[36:37] op_sel_hi:[0,1,1]
	s_waitcnt lgkmcnt(0)
	v_mov_b32_e32 v127, v18
	v_mov_b32_e32 v18, v7
	v_mov_b32_e32 v124, v8
	v_mov_b32_e32 v125, v20
	v_mov_b32_e32 v20, v9
	ds_read_b128 v[6:9], v6
	ds_read_b128 v[22:25], v10
	s_add_i32 s34, s83, 0xffff4030
	s_add_i32 s58, s83, 0xffff5030
	v_pk_fma_f32 v[100:101], v[208:209], v[16:17], v[14:15] op_sel_hi:[0,1,1]
	s_waitcnt lgkmcnt(1)
	v_mov_b32_e32 v130, v6
	s_waitcnt lgkmcnt(0)
	v_mov_b32_e32 v131, v22
	v_mov_b32_e32 v22, v7
	v_mov_b32_e32 v6, s34
	v_mov_b32_e32 v7, s58
	v_mov_b32_e32 v128, v8
	v_mov_b32_e32 v129, v24
	v_mov_b32_e32 v24, v9
	ds_read_b128 v[10:13], v7
	ds_read_b128 v[6:9], v6
	s_add_i32 s34, s83, 0xffff6030
	s_add_i32 s58, s83, 0xffff7030
	v_pk_add_f32 v[46:47], v[60:61], v[102:103]
	s_waitcnt lgkmcnt(1)
	v_mov_b32_e32 v134, v10
	s_waitcnt lgkmcnt(0)
	v_mov_b32_e32 v135, v6
	v_mov_b32_e32 v6, v11
	v_mov_b32_e32 v10, s34
	v_mov_b32_e32 v11, s58
	v_mov_b32_e32 v132, v12
	v_mov_b32_e32 v133, v8
	v_mov_b32_e32 v8, v13
	ds_read_b128 v[14:17], v11
	ds_read_b128 v[10:13], v10
	s_add_i32 s34, s83, 0xffff8030
	s_add_i32 s58, s83, 0xffff9030
	v_pk_add_f32 v[48:49], v[58:59], v[104:105]
	s_waitcnt lgkmcnt(1)
	v_mov_b32_e32 v138, v14
	s_waitcnt lgkmcnt(0)
	v_mov_b32_e32 v139, v10
	v_mov_b32_e32 v10, v15
	v_mov_b32_e32 v14, s34
	v_mov_b32_e32 v15, s58
	v_mov_b32_e32 v136, v16
	v_mov_b32_e32 v137, v12
	v_mov_b32_e32 v12, v17
	ds_read_b128 v[26:29], v15
	ds_read_b128 v[14:17], v14
	s_add_i32 s34, s83, 0xffffa030
	s_add_i32 s58, s83, 0xffffb030
	v_pk_add_f32 v[50:51], v[56:57], v[106:107]
	s_waitcnt lgkmcnt(1)
	v_mov_b32_e32 v142, v26
	s_waitcnt lgkmcnt(0)
; #define LAS __attribute__((address_space(3)))
; __device__ __forceinline__ void adaln_unit(const Args& a, LAS unsigned char* lds, int unit, int tid, int wave, int lane) {
;     ...
;         for (int k = 0; k < 128; k += 16) {
;             float w[16];
; #pragma unroll
;             for (int e = 0; e < 16; ++e) w[e] = W[(size_t)(kh * 1024 + kb + k + e) * N + jc];
; #pragma unroll
;             for (int q = 0; q < 4; ++q)
; #pragma unroll
;                 for (int r = 0; r < 18; ++r) { const f32x4 s = *(const LAS f32x4*)(sc + r * 1024 + kb + k + 4 * q); acc[r] += s[0] * w[4 * q] + s[1] * w[4 * q + 1] + s[2] * w[4 * q + 2] + s[3] * w[4 * q + 3]; }
;         }
;     }
; #pragma unroll
;     for (int r = 0; r < 18; ++r) red[(wave * 18 + r) * 64 + lane] = acc[r];
;     __syncthreads();
;     for (int i = tid; i < 18 * 64; i += NTHR) { const int r = i >> 6, l = i & 63; float s = 0.f;
	v_mov_b32_e32 v143, v14
	v_mov_b32_e32 v14, v27
	v_mov_b32_e32 v26, s34
	v_mov_b32_e32 v27, s58
	v_mov_b32_e32 v140, v28
	v_mov_b32_e32 v141, v16
	v_mov_b32_e32 v16, v29
	ds_read_b128 v[30:33], v27
	ds_read_b128 v[26:29], v26
	s_add_i32 s34, s83, 0xffffc030
	s_add_i32 s58, s83, 0xffffd030
	v_pk_add_f32 v[66:67], v[66:67], v[112:113]
	s_waitcnt lgkmcnt(1)
	v_mov_b32_e32 v144, v30
	s_waitcnt lgkmcnt(0)
	v_mov_b32_e32 v145, v26
	v_mov_b32_e32 v26, v31
	v_mov_b32_e32 v30, s34
	v_mov_b32_e32 v31, s58
	v_mov_b32_e32 v154, v32
	v_mov_b32_e32 v155, v28
	v_mov_b32_e32 v28, v33
	ds_read_b128 v[34:37], v31
	ds_read_b128 v[30:33], v30
	s_add_i32 s58, s83, 0xfffff030
	s_add_i32 s34, s83, 0xffffe030
	v_pk_add_f32 v[68:69], v[68:69], v[114:115]
	s_waitcnt lgkmcnt(1)
	v_mov_b32_e32 v156, v34
	s_waitcnt lgkmcnt(0)
	v_mov_b32_e32 v157, v30
	v_mov_b32_e32 v30, v35
	v_mov_b32_e32 v35, s58
	ds_read_b128 v[150:153], v35
	v_mov_b32_e32 v34, s34
	v_mov_b32_e32 v158, v36
	v_mov_b32_e32 v159, v32
	v_mov_b32_e32 v32, v37
	s_waitcnt lgkmcnt(0)
	v_mov_b32_e32 v160, v150
	v_mov_b32_e32 v150, v152
	s_nop 0
	ds_read_b128 v[34:37], v34
	v_lshl_add_u64 v[122:123], v[122:123], 0, s[74:75]
	v_pk_add_f32 v[70:71], v[70:71], v[116:117]
	s_add_i32 s83, s83, 64
	s_cmpk_lt_u32 s82, 0x70
	s_waitcnt lgkmcnt(0)
	v_mov_b32_e32 v161, v34
	v_mov_b32_e32 v34, v151
	v_mov_b32_e32 v151, v36
	v_mov_b32_e32 v36, v153
	s_waitcnt vmcnt(2)
	v_pk_mul_f32 v[18:19], v[212:213], v[18:19] op_sel_hi:[0,1]
	v_pk_mul_f32 v[22:23], v[212:213], v[22:23] op_sel_hi:[0,1]
	v_pk_mul_f32 v[6:7], v[212:213], v[6:7] op_sel_hi:[0,1]
	v_pk_mul_f32 v[10:11], v[212:213], v[10:11] op_sel_hi:[0,1]
	v_pk_mul_f32 v[14:15], v[212:213], v[14:15] op_sel_hi:[0,1]
	v_pk_mul_f32 v[26:27], v[212:213], v[26:27] op_sel_hi:[0,1]
	v_pk_mul_f32 v[30:31], v[212:213], v[30:31] op_sel_hi:[0,1]
	v_pk_mul_f32 v[34:35], v[212:213], v[34:35] op_sel_hi:[0,1]
	v_pk_mul_f32 v[2:3], v[212:213], v[2:3] op_sel_hi:[0,1]
	v_pk_fma_f32 v[18:19], v[210:211], v[126:127], v[18:19] op_sel_hi:[0,1,1]
	v_pk_fma_f32 v[22:23], v[210:211], v[130:131], v[22:23] op_sel_hi:[0,1,1]
	v_pk_fma_f32 v[6:7], v[210:211], v[134:135], v[6:7] op_sel_hi:[0,1,1]
	v_pk_fma_f32 v[10:11], v[210:211], v[138:139], v[10:11] op_sel_hi:[0,1,1]
	v_pk_fma_f32 v[14:15], v[210:211], v[142:143], v[14:15] op_sel_hi:[0,1,1]
	v_pk_fma_f32 v[26:27], v[210:211], v[144:145], v[26:27] op_sel_hi:[0,1,1]
	v_pk_fma_f32 v[30:31], v[210:211], v[156:157], v[30:31] op_sel_hi:[0,1,1]
	v_pk_fma_f32 v[34:35], v[210:211], v[160:161], v[34:35] op_sel_hi:[0,1,1]
	v_pk_fma_f32 v[120:121], v[210:211], v[120:121], v[2:3] op_sel_hi:[0,1,1]
	s_nop 0
	s_waitcnt vmcnt(1)
	v_pk_fma_f32 v[124:125], v[214:215], v[124:125], v[18:19] op_sel_hi:[0,1,1]
	v_pk_fma_f32 v[18:19], v[214:215], v[158:159], v[30:31] op_sel_hi:[0,1,1]
	v_lshl_add_u64 v[30:31], v[122:123], 0, s[74:75]
	s_nop 0
	v_pk_fma_f32 v[126:127], v[214:215], v[128:129], v[22:23] op_sel_hi:[0,1,1]
	v_pk_fma_f32 v[22:23], v[214:215], v[150:151], v[34:35] op_sel_hi:[0,1,1]
	v_pk_add_f32 v[34:35], v[62:63], v[64:65]
	v_pk_fma_f32 v[2:3], v[214:215], v[132:133], v[6:7] op_sel_hi:[0,1,1]
	v_pk_fma_f32 v[6:7], v[214:215], v[136:137], v[10:11] op_sel_hi:[0,1,1]
	v_pk_fma_f32 v[10:11], v[214:215], v[140:141], v[14:15] op_sel_hi:[0,1,1]
	v_pk_fma_f32 v[14:15], v[214:215], v[154:155], v[26:27] op_sel_hi:[0,1,1]
	v_pk_fma_f32 v[26:27], v[214:215], v[118:119], v[120:121] op_sel_hi:[0,1,1]
	v_pk_add_f32 v[34:35], v[34:35], v[82:83]
	v_pk_add_f32 v[62:63], v[52:53], v[92:93]
	v_pk_add_f32 v[34:35], v[34:35], v[100:101]
	v_pk_add_f32 v[52:53], v[54:55], v[108:109]
	v_pk_add_f32 v[64:65], v[62:63], v[110:111]
	s_waitcnt vmcnt(0)
	v_pk_fma_f32 v[20:21], v[216:217], v[20:21], v[124:125] op_sel_hi:[0,1,1]
	v_pk_fma_f32 v[24:25], v[216:217], v[24:25], v[126:127] op_sel_hi:[0,1,1]
	v_pk_fma_f32 v[2:3], v[216:217], v[8:9], v[2:3] op_sel_hi:[0,1,1]
	v_pk_fma_f32 v[6:7], v[216:217], v[12:13], v[6:7] op_sel_hi:[0,1,1]
	v_pk_fma_f32 v[8:9], v[216:217], v[16:17], v[10:11] op_sel_hi:[0,1,1]
	v_pk_fma_f32 v[10:11], v[216:217], v[28:29], v[14:15] op_sel_hi:[0,1,1]
	v_pk_fma_f32 v[12:13], v[216:217], v[32:33], v[18:19] op_sel_hi:[0,1,1]
	v_pk_fma_f32 v[14:15], v[216:217], v[36:37], v[22:23] op_sel_hi:[0,1,1]
	v_pk_fma_f32 v[4:5], v[216:217], v[4:5], v[26:27] op_sel_hi:[0,1,1]
	v_pk_add_f32 v[62:63], v[34:35], v[20:21]
	v_pk_add_f32 v[60:61], v[46:47], v[24:25]
	v_pk_add_f32 v[58:59], v[48:49], v[2:3]
	v_pk_add_f32 v[56:57], v[50:51], v[6:7]
	v_pk_add_f32 v[54:55], v[52:53], v[8:9]
	v_pk_add_f32 v[52:53], v[64:65], v[10:11]
	v_pk_add_f32 v[50:51], v[66:67], v[12:13]
	v_pk_add_f32 v[48:49], v[68:69], v[14:15]
	v_pk_add_f32 v[46:47], v[70:71], v[4:5]
	s_cbranch_scc1 .LBB0_20
	s_movk_i32 s58, 0x400
	s_mov_b64 s[82:83], 0
	s_and_b64 vcc, exec, s[80:81]
	s_cbranch_vccz .LBB0_12
	ds_write2st64_b32 v146, v63, v62 offset1:1
	ds_write2st64_b32 v146, v61, v60 offset0:2 offset1:3
	ds_write2st64_b32 v146, v59, v58 offset0:4 offset1:5
	ds_write2st64_b32 v146, v57, v56 offset0:6 offset1:7
	ds_write2st64_b32 v146, v55, v54 offset0:8 offset1:9
	ds_write2st64_b32 v146, v53, v52 offset0:10 offset1:11
	ds_write2st64_b32 v146, v51, v50 offset0:12 offset1:13
	ds_write2st64_b32 v146, v49, v48 offset0:14 offset1:15
	ds_write2st64_b32 v146, v47, v46 offset0:16 offset1:17
	s_waitcnt lgkmcnt(0)
	s_barrier
	s_and_saveexec_b64 s[78:79], s[4:5]
	s_cbranch_execz .LBB0_10
	v_or_b32_e32 v2, s28, v147
	v_ashrrev_i32_e32 v3, 31, v2
	s_mov_b64 s[80:81], 0
	v_mov_b32_e32 v12, v41
	s_branch .LBB0_25
